# prep: S5 Toeplitz-kernel loop re-associated (C*B product held in registers across the 16 powers per thread), f32 math unchanged
# baseline (speedup 1.0000x reference)
.LBB0_30:
	global_load_dword v75, v[66:67], off
	global_load_dword v76, v[68:69], off
	global_load_dword v77, v[70:71], off
	global_load_dword v78, v[72:73], off
	v_and_b32_e32 v79, 0x7e, v0
	s_add_i32 s14, 0, 0x10200
	v_lshl_or_b32 v80, v0, 2, 4
	v_lshl_add_u32 v79, v79, 2, s14
	v_add_u32_e32 v80, s14, v80
	ds_read_b32 v79, v79
	ds_read_b32 v80, v80
	v_add_co_u32_e32 v64, vcc, 0x200, v64
	s_xor_b64 s[14:15], vcc, -1
	s_and_b64 s[14:15], exec, s[14:15]
	v_add_u32_e32 v0, 64, v0
	v_lshl_add_u64 v[66:67], v[66:67], 0, s[44:45]
	v_lshl_add_u64 v[68:69], v[68:69], 0, s[44:45]
	v_lshl_add_u64 v[70:71], v[70:71], 0, s[44:45]
	v_lshl_add_u64 v[72:73], v[72:73], 0, s[44:45]
	s_or_b64 s[0:1], s[14:15], s[0:1]
	s_waitcnt vmcnt(2) lgkmcnt(0)
	v_mul_f32_e32 v81, v76, v80
	v_mul_f32_e32 v80, v75, v80
	v_fma_f32 v75, v75, v79, -v81
	v_fmac_f32_e32 v80, v76, v79
	s_waitcnt vmcnt(0)
	ds_write2st64_b32 v74, v77, v78 offset0:32 offset1:48
	ds_write2st64_b32 v74, v75, v80 offset1:16
	v_add_u32_e32 v74, 0x800, v74
	s_andn2_b64 exec, exec, s[0:1]
	s_cbranch_execnz .LBB0_30
	s_or_b64 exec, exec, s[0:1]
	s_ashr_i32 s64, s62, 5
	s_and_b32 s43, s62, 31
	s_lshl_b32 s0, s64, 9
	s_lshl_b32 s1, s43, 4
	s_or_b32 s46, s1, s0
	s_mov_b64 s[0:1], 0
	v_mov_b32_e32 v0, v88
	v_mov_b32_e32 v64, v173
	s_waitcnt lgkmcnt(0)
	s_barrier
	ds_read_b128 v[100:103], v90 offset:0
	ds_read_b128 v[104:107], v90 offset:16
	ds_read_b128 v[108:111], v90 offset:4096
	ds_read_b128 v[112:115], v90 offset:4112
	v_add_u32_e32 v78, 0, v89
	v_add_u32_e32 v79, 0x1000, v78
	ds_read2_b32 v[116:117], v78 offset0:0 offset1:16
	ds_read2_b32 v[118:119], v78 offset0:32 offset1:48
	ds_read2_b32 v[120:121], v78 offset0:64 offset1:80
	ds_read2_b32 v[122:123], v78 offset0:96 offset1:112
	ds_read2_b32 v[70:71], v79 offset0:0 offset1:16
	ds_read2_b32 v[72:73], v79 offset0:32 offset1:48
	ds_read2_b32 v[74:75], v79 offset0:64 offset1:80
	ds_read2_b32 v[76:77], v79 offset0:96 offset1:112
	s_waitcnt lgkmcnt(0)
	v_mul_f32_e32 v66, v108, v70
	v_mul_f32_e32 v68, v100, v70
	v_fma_f32 v124, v100, v116, -v66
	v_fma_f32 v125, v108, v116, v68
	v_mul_f32_e32 v66, v109, v71
	v_mul_f32_e32 v68, v101, v71
	v_fma_f32 v126, v101, v117, -v66
	v_fma_f32 v127, v109, v117, v68
	v_mul_f32_e32 v66, v110, v72
	v_mul_f32_e32 v68, v102, v72
	v_fma_f32 v128, v102, v118, -v66
	v_fma_f32 v129, v110, v118, v68
	v_mul_f32_e32 v66, v111, v73
	v_mul_f32_e32 v68, v103, v73
	v_fma_f32 v130, v103, v119, -v66
	v_fma_f32 v131, v111, v119, v68
	v_mul_f32_e32 v66, v112, v74
	v_mul_f32_e32 v68, v104, v74
	v_fma_f32 v132, v104, v120, -v66
	v_fma_f32 v133, v112, v120, v68
	v_mul_f32_e32 v66, v113, v75
	v_mul_f32_e32 v68, v105, v75
	v_fma_f32 v134, v105, v121, -v66
	v_fma_f32 v135, v113, v121, v68
	v_mul_f32_e32 v66, v114, v76
	v_mul_f32_e32 v68, v106, v76
	v_fma_f32 v136, v106, v122, -v66
	v_fma_f32 v137, v114, v122, v68
	v_mul_f32_e32 v66, v115, v77
	v_mul_f32_e32 v68, v107, v77
	v_fma_f32 v138, v107, v123, -v66
	v_fma_f32 v139, v115, v123, v68
	ds_read_b128 v[100:103], v90 offset:32
	ds_read_b128 v[104:107], v90 offset:48
	ds_read_b128 v[108:111], v90 offset:4128
	ds_read_b128 v[112:115], v90 offset:4144
	v_add_u32_e32 v78, 0x200, v89
	v_add_u32_e32 v79, 0x1000, v78
	ds_read2_b32 v[116:117], v78 offset0:0 offset1:16
	ds_read2_b32 v[118:119], v78 offset0:32 offset1:48
	ds_read2_b32 v[120:121], v78 offset0:64 offset1:80
	ds_read2_b32 v[122:123], v78 offset0:96 offset1:112
	ds_read2_b32 v[70:71], v79 offset0:0 offset1:16
	ds_read2_b32 v[72:73], v79 offset0:32 offset1:48
	ds_read2_b32 v[74:75], v79 offset0:64 offset1:80
	ds_read2_b32 v[76:77], v79 offset0:96 offset1:112
	s_waitcnt lgkmcnt(0)
	v_mul_f32_e32 v66, v108, v70
	v_mul_f32_e32 v68, v100, v70
	v_fma_f32 v140, v100, v116, -v66
	v_fma_f32 v141, v108, v116, v68
	v_mul_f32_e32 v66, v109, v71
	v_mul_f32_e32 v68, v101, v71
	v_fma_f32 v142, v101, v117, -v66
	v_fma_f32 v143, v109, v117, v68
	v_mul_f32_e32 v66, v110, v72
	v_mul_f32_e32 v68, v102, v72
	v_fma_f32 v144, v102, v118, -v66
	v_fma_f32 v145, v110, v118, v68
	v_mul_f32_e32 v66, v111, v73
	v_mul_f32_e32 v68, v103, v73
	v_fma_f32 v146, v103, v119, -v66
	v_fma_f32 v147, v111, v119, v68
	v_mul_f32_e32 v66, v112, v74
	v_mul_f32_e32 v68, v104, v74
	v_fma_f32 v148, v104, v120, -v66
	v_fma_f32 v149, v112, v120, v68
	v_mul_f32_e32 v66, v113, v75
	v_mul_f32_e32 v68, v105, v75
	v_fma_f32 v150, v105, v121, -v66
	v_fma_f32 v151, v113, v121, v68
	v_mul_f32_e32 v66, v114, v76
	v_mul_f32_e32 v68, v106, v76
	v_fma_f32 v152, v106, v122, -v66
	v_fma_f32 v80, v114, v122, v68
	v_mul_f32_e32 v66, v115, v77
	v_mul_f32_e32 v68, v107, v77
	v_fma_f32 v154, v107, v123, -v66
	v_fma_f32 v155, v115, v123, v68
	ds_read_b128 v[100:103], v90 offset:64
	ds_read_b128 v[104:107], v90 offset:80
	ds_read_b128 v[108:111], v90 offset:4160
	ds_read_b128 v[112:115], v90 offset:4176
	v_add_u32_e32 v78, 0x400, v89
	v_add_u32_e32 v79, 0x1000, v78
	ds_read2_b32 v[116:117], v78 offset0:0 offset1:16
	ds_read2_b32 v[118:119], v78 offset0:32 offset1:48
	ds_read2_b32 v[120:121], v78 offset0:64 offset1:80
	ds_read2_b32 v[122:123], v78 offset0:96 offset1:112
	ds_read2_b32 v[70:71], v79 offset0:0 offset1:16
	ds_read2_b32 v[72:73], v79 offset0:32 offset1:48
	ds_read2_b32 v[74:75], v79 offset0:64 offset1:80
	ds_read2_b32 v[76:77], v79 offset0:96 offset1:112
	s_waitcnt lgkmcnt(0)
	v_mul_f32_e32 v66, v108, v70
	v_mul_f32_e32 v68, v100, v70
	v_fma_f32 v156, v100, v116, -v66
	v_fma_f32 v157, v108, v116, v68
	v_mul_f32_e32 v66, v109, v71
	v_mul_f32_e32 v68, v101, v71
	v_fma_f32 v158, v101, v117, -v66
	v_fma_f32 v159, v109, v117, v68
	v_mul_f32_e32 v66, v110, v72
	v_mul_f32_e32 v68, v102, v72
	v_fma_f32 v160, v102, v118, -v66
	v_fma_f32 v161, v110, v118, v68
	v_mul_f32_e32 v66, v111, v73
	v_mul_f32_e32 v68, v103, v73
	v_fma_f32 v162, v103, v119, -v66
	v_fma_f32 v163, v111, v119, v68
	v_mul_f32_e32 v66, v112, v74
	v_mul_f32_e32 v68, v104, v74
	v_fma_f32 v164, v104, v120, -v66
	v_fma_f32 v165, v112, v120, v68
	v_mul_f32_e32 v66, v113, v75
	v_mul_f32_e32 v68, v105, v75
	v_fma_f32 v166, v105, v121, -v66
	v_fma_f32 v167, v113, v121, v68
	v_mul_f32_e32 v66, v114, v76
	v_mul_f32_e32 v68, v106, v76
	v_fma_f32 v168, v106, v122, -v66
	v_fma_f32 v169, v114, v122, v68
	v_mul_f32_e32 v66, v115, v77
	v_mul_f32_e32 v68, v107, v77
	v_fma_f32 v170, v107, v123, -v66
	v_fma_f32 v171, v115, v123, v68
	ds_read_b128 v[100:103], v90 offset:96
	ds_read_b128 v[104:107], v90 offset:112
	ds_read_b128 v[108:111], v90 offset:4192
	ds_read_b128 v[112:115], v90 offset:4208
	v_add_u32_e32 v78, 0x600, v89
	v_add_u32_e32 v79, 0x1000, v78
	ds_read2_b32 v[116:117], v78 offset0:0 offset1:16
	ds_read2_b32 v[118:119], v78 offset0:32 offset1:48
	ds_read2_b32 v[120:121], v78 offset0:64 offset1:80
	ds_read2_b32 v[122:123], v78 offset0:96 offset1:112
	ds_read2_b32 v[70:71], v79 offset0:0 offset1:16
	ds_read2_b32 v[72:73], v79 offset0:32 offset1:48
	ds_read2_b32 v[74:75], v79 offset0:64 offset1:80
	ds_read2_b32 v[76:77], v79 offset0:96 offset1:112
	s_waitcnt lgkmcnt(0)
	v_mul_f32_e32 v66, v108, v70
	v_mul_f32_e32 v68, v100, v70
	v_fma_f32 v172, v100, v116, -v66
	v_fma_f32 v81, v108, v116, v68
	v_mul_f32_e32 v66, v109, v71
	v_mul_f32_e32 v68, v101, v71
	v_fma_f32 v174, v101, v117, -v66
	v_fma_f32 v175, v109, v117, v68
	v_mul_f32_e32 v66, v110, v72
	v_mul_f32_e32 v68, v102, v72
	v_fma_f32 v176, v102, v118, -v66
	v_fma_f32 v177, v110, v118, v68
	v_mul_f32_e32 v66, v111, v73
	v_mul_f32_e32 v68, v103, v73
	v_fma_f32 v178, v103, v119, -v66
	v_fma_f32 v179, v111, v119, v68
	v_mul_f32_e32 v66, v112, v74
	v_mul_f32_e32 v68, v104, v74
	v_fma_f32 v180, v104, v120, -v66
	v_fma_f32 v181, v112, v120, v68
	v_mul_f32_e32 v66, v113, v75
	v_mul_f32_e32 v68, v105, v75
	v_fma_f32 v182, v105, v121, -v66
	v_fma_f32 v183, v113, v121, v68
	v_mul_f32_e32 v66, v114, v76
	v_mul_f32_e32 v68, v106, v76
	v_fma_f32 v184, v106, v122, -v66
	v_fma_f32 v185, v114, v122, v68
	v_mul_f32_e32 v66, v115, v77
	v_mul_f32_e32 v68, v107, v77
	v_fma_f32 v186, v107, v123, -v66
	v_fma_f32 v187, v115, v123, v68
	ds_read_b128 v[100:103], v90 offset:128
	ds_read_b128 v[104:107], v90 offset:144
	ds_read_b128 v[108:111], v90 offset:4224
	ds_read_b128 v[112:115], v90 offset:4240
	v_add_u32_e32 v78, 0x800, v89
	v_add_u32_e32 v79, 0x1000, v78
	ds_read2_b32 v[116:117], v78 offset0:0 offset1:16
	ds_read2_b32 v[118:119], v78 offset0:32 offset1:48
	ds_read2_b32 v[120:121], v78 offset0:64 offset1:80
	ds_read2_b32 v[122:123], v78 offset0:96 offset1:112
	ds_read2_b32 v[70:71], v79 offset0:0 offset1:16
	ds_read2_b32 v[72:73], v79 offset0:32 offset1:48
	ds_read2_b32 v[74:75], v79 offset0:64 offset1:80
	ds_read2_b32 v[76:77], v79 offset0:96 offset1:112
	s_waitcnt lgkmcnt(0)
	v_mul_f32_e32 v66, v108, v70
	v_mul_f32_e32 v68, v100, v70
	v_fma_f32 v188, v100, v116, -v66
	v_fma_f32 v189, v108, v116, v68
	v_mul_f32_e32 v66, v109, v71
	v_mul_f32_e32 v68, v101, v71
	v_fma_f32 v190, v101, v117, -v66
	v_fma_f32 v191, v109, v117, v68
	v_mul_f32_e32 v66, v110, v72
	v_mul_f32_e32 v68, v102, v72
	v_fma_f32 v192, v102, v118, -v66
	v_fma_f32 v193, v110, v118, v68
	v_mul_f32_e32 v66, v111, v73
	v_mul_f32_e32 v68, v103, v73
	v_fma_f32 v194, v103, v119, -v66
	v_fma_f32 v195, v111, v119, v68
	v_mul_f32_e32 v66, v112, v74
	v_mul_f32_e32 v68, v104, v74
	v_fma_f32 v196, v104, v120, -v66
	v_fma_f32 v197, v112, v120, v68
	v_mul_f32_e32 v66, v113, v75
	v_mul_f32_e32 v68, v105, v75
	v_fma_f32 v198, v105, v121, -v66
	v_fma_f32 v199, v113, v121, v68
	v_mul_f32_e32 v66, v114, v76
	v_mul_f32_e32 v68, v106, v76
	v_fma_f32 v200, v106, v122, -v66
	v_fma_f32 v201, v114, v122, v68
	v_mul_f32_e32 v66, v115, v77
	v_mul_f32_e32 v68, v107, v77
	v_fma_f32 v202, v107, v123, -v66
	v_fma_f32 v203, v115, v123, v68
	ds_read_b128 v[100:103], v90 offset:160
	ds_read_b128 v[104:107], v90 offset:176
	ds_read_b128 v[108:111], v90 offset:4256
	ds_read_b128 v[112:115], v90 offset:4272
	v_add_u32_e32 v78, 0xa00, v89
	v_add_u32_e32 v79, 0x1000, v78
	ds_read2_b32 v[116:117], v78 offset0:0 offset1:16
	ds_read2_b32 v[118:119], v78 offset0:32 offset1:48
	ds_read2_b32 v[120:121], v78 offset0:64 offset1:80
	ds_read2_b32 v[122:123], v78 offset0:96 offset1:112
	ds_read2_b32 v[70:71], v79 offset0:0 offset1:16
	ds_read2_b32 v[72:73], v79 offset0:32 offset1:48
	ds_read2_b32 v[74:75], v79 offset0:64 offset1:80
	ds_read2_b32 v[76:77], v79 offset0:96 offset1:112
	s_waitcnt lgkmcnt(0)
	v_mul_f32_e32 v66, v108, v70
	v_mul_f32_e32 v68, v100, v70
	v_fma_f32 v204, v100, v116, -v66
	v_fma_f32 v205, v108, v116, v68
	v_mul_f32_e32 v66, v109, v71
	v_mul_f32_e32 v68, v101, v71
	v_fma_f32 v206, v101, v117, -v66
	v_fma_f32 v207, v109, v117, v68
	v_mul_f32_e32 v66, v110, v72
	v_mul_f32_e32 v68, v102, v72
	v_fma_f32 v208, v102, v118, -v66
	v_fma_f32 v209, v110, v118, v68
	v_mul_f32_e32 v66, v111, v73
	v_mul_f32_e32 v68, v103, v73
	v_fma_f32 v210, v103, v119, -v66
	v_fma_f32 v211, v111, v119, v68
	v_mul_f32_e32 v66, v112, v74
	v_mul_f32_e32 v68, v104, v74
	v_fma_f32 v212, v104, v120, -v66
	v_fma_f32 v213, v112, v120, v68
	v_mul_f32_e32 v66, v113, v75
	v_mul_f32_e32 v68, v105, v75
	v_fma_f32 v214, v105, v121, -v66
	v_fma_f32 v215, v113, v121, v68
	v_mul_f32_e32 v66, v114, v76
	v_mul_f32_e32 v68, v106, v76
	v_fma_f32 v216, v106, v122, -v66
	v_fma_f32 v217, v114, v122, v68
	v_mul_f32_e32 v66, v115, v77
	v_mul_f32_e32 v68, v107, v77
	v_fma_f32 v218, v107, v123, -v66
	v_fma_f32 v219, v115, v123, v68
	ds_read_b128 v[100:103], v90 offset:192
	ds_read_b128 v[104:107], v90 offset:208
	ds_read_b128 v[108:111], v90 offset:4288
	ds_read_b128 v[112:115], v90 offset:4304
	v_add_u32_e32 v78, 0xc00, v89
	v_add_u32_e32 v79, 0x1000, v78
	ds_read2_b32 v[116:117], v78 offset0:0 offset1:16
	ds_read2_b32 v[118:119], v78 offset0:32 offset1:48
	ds_read2_b32 v[120:121], v78 offset0:64 offset1:80
	ds_read2_b32 v[122:123], v78 offset0:96 offset1:112
	ds_read2_b32 v[70:71], v79 offset0:0 offset1:16
	ds_read2_b32 v[72:73], v79 offset0:32 offset1:48
	ds_read2_b32 v[74:75], v79 offset0:64 offset1:80
	ds_read2_b32 v[76:77], v79 offset0:96 offset1:112
	s_waitcnt lgkmcnt(0)
	v_mul_f32_e32 v66, v108, v70
	v_mul_f32_e32 v68, v100, v70
	v_fma_f32 v220, v100, v116, -v66
	v_fma_f32 v221, v108, v116, v68
	v_mul_f32_e32 v66, v109, v71
	v_mul_f32_e32 v68, v101, v71
	v_fma_f32 v222, v101, v117, -v66
	v_fma_f32 v223, v109, v117, v68
	v_mul_f32_e32 v66, v110, v72
	v_mul_f32_e32 v68, v102, v72
	v_fma_f32 v224, v102, v118, -v66
	v_fma_f32 v225, v110, v118, v68
	v_mul_f32_e32 v66, v111, v73
	v_mul_f32_e32 v68, v103, v73
	v_fma_f32 v226, v103, v119, -v66
	v_fma_f32 v227, v111, v119, v68
	v_mul_f32_e32 v66, v112, v74
	v_mul_f32_e32 v68, v104, v74
	v_fma_f32 v228, v104, v120, -v66
	v_fma_f32 v229, v112, v120, v68
	v_mul_f32_e32 v66, v113, v75
	v_mul_f32_e32 v68, v105, v75
	v_fma_f32 v230, v105, v121, -v66
	v_fma_f32 v231, v113, v121, v68
	v_mul_f32_e32 v66, v114, v76
	v_mul_f32_e32 v68, v106, v76
	v_fma_f32 v232, v106, v122, -v66
	v_fma_f32 v233, v114, v122, v68
	v_mul_f32_e32 v66, v115, v77
	v_mul_f32_e32 v68, v107, v77
	v_fma_f32 v234, v107, v123, -v66
	v_fma_f32 v235, v115, v123, v68
	ds_read_b128 v[100:103], v90 offset:224
	ds_read_b128 v[104:107], v90 offset:240
	ds_read_b128 v[108:111], v90 offset:4320
	ds_read_b128 v[112:115], v90 offset:4336
	v_add_u32_e32 v78, 0xe00, v89
	v_add_u32_e32 v79, 0x1000, v78
	ds_read2_b32 v[116:117], v78 offset0:0 offset1:16
	ds_read2_b32 v[118:119], v78 offset0:32 offset1:48
	ds_read2_b32 v[120:121], v78 offset0:64 offset1:80
	ds_read2_b32 v[122:123], v78 offset0:96 offset1:112
	ds_read2_b32 v[70:71], v79 offset0:0 offset1:16
	ds_read2_b32 v[72:73], v79 offset0:32 offset1:48
	ds_read2_b32 v[74:75], v79 offset0:64 offset1:80
	ds_read2_b32 v[76:77], v79 offset0:96 offset1:112
	s_waitcnt lgkmcnt(0)
	v_mul_f32_e32 v66, v108, v70
	v_mul_f32_e32 v68, v100, v70
	v_fma_f32 v236, v100, v116, -v66
	v_fma_f32 v237, v108, v116, v68
	v_mul_f32_e32 v66, v109, v71
	v_mul_f32_e32 v68, v101, v71
	v_fma_f32 v238, v101, v117, -v66
	v_fma_f32 v239, v109, v117, v68
	v_mul_f32_e32 v66, v110, v72
	v_mul_f32_e32 v68, v102, v72
	v_fma_f32 v240, v102, v118, -v66
	v_fma_f32 v241, v110, v118, v68
	v_mul_f32_e32 v66, v111, v73
	v_mul_f32_e32 v68, v103, v73
	v_fma_f32 v242, v103, v119, -v66
	v_fma_f32 v243, v111, v119, v68
	v_mul_f32_e32 v66, v112, v74
	v_mul_f32_e32 v68, v104, v74
	v_fma_f32 v244, v104, v120, -v66
	v_fma_f32 v245, v112, v120, v68
	v_mul_f32_e32 v66, v113, v75
	v_mul_f32_e32 v68, v105, v75
	v_fma_f32 v246, v105, v121, -v66
	v_fma_f32 v247, v113, v121, v68
	v_mul_f32_e32 v66, v114, v76
	v_mul_f32_e32 v68, v106, v76
	v_fma_f32 v248, v106, v122, -v66
	v_fma_f32 v249, v114, v122, v68
	v_mul_f32_e32 v66, v115, v77
	v_mul_f32_e32 v68, v107, v77
	v_fma_f32 v250, v107, v123, -v66
	v_fma_f32 v251, v115, v123, v68
	s_branch .LBB0_33

.LBB0_33:
	v_and_b32_e32 v66, 31, v0
	v_lshl_add_u32 v67, v66, 8, 0
	v_mov_b32_e32 v66, 0
	v_mov_b32_e32 v68, 0
	ds_read_b128 v[100:103], v67 offset:0
	ds_read_b128 v[104:107], v67 offset:16
	ds_read_b128 v[108:111], v67 offset:8448
	ds_read_b128 v[112:115], v67 offset:8464
	ds_read_b128 v[116:119], v67 offset:32
	ds_read_b128 v[120:123], v67 offset:48
	ds_read_b128 v[70:73], v67 offset:8480
	ds_read_b128 v[74:77], v67 offset:8496
	s_waitcnt lgkmcnt(4)
	v_fmac_f32_e32 v66, v100, v124
	v_fmac_f32_e32 v68, v108, v125
	v_fmac_f32_e32 v66, v101, v126
	v_fmac_f32_e32 v68, v109, v127
	v_fmac_f32_e32 v66, v102, v128
	v_fmac_f32_e32 v68, v110, v129
	v_fmac_f32_e32 v66, v103, v130
	v_fmac_f32_e32 v68, v111, v131
	v_fmac_f32_e32 v66, v104, v132
	v_fmac_f32_e32 v68, v112, v133
	v_fmac_f32_e32 v66, v105, v134
	v_fmac_f32_e32 v68, v113, v135
	v_fmac_f32_e32 v66, v106, v136
	v_fmac_f32_e32 v68, v114, v137
	v_fmac_f32_e32 v66, v107, v138
	v_fmac_f32_e32 v68, v115, v139
	ds_read_b128 v[100:103], v67 offset:64
	ds_read_b128 v[104:107], v67 offset:80
	ds_read_b128 v[108:111], v67 offset:8512
	ds_read_b128 v[112:115], v67 offset:8528
	s_waitcnt lgkmcnt(4)
	v_fmac_f32_e32 v66, v116, v140
	v_fmac_f32_e32 v68, v70, v141
	v_fmac_f32_e32 v66, v117, v142
	v_fmac_f32_e32 v68, v71, v143
	v_fmac_f32_e32 v66, v118, v144
	v_fmac_f32_e32 v68, v72, v145
	v_fmac_f32_e32 v66, v119, v146
	v_fmac_f32_e32 v68, v73, v147
	v_fmac_f32_e32 v66, v120, v148
	v_fmac_f32_e32 v68, v74, v149
	v_fmac_f32_e32 v66, v121, v150
	v_fmac_f32_e32 v68, v75, v151
	v_fmac_f32_e32 v66, v122, v152
	v_fmac_f32_e32 v68, v76, v80
	v_fmac_f32_e32 v66, v123, v154
	v_fmac_f32_e32 v68, v77, v155
	ds_read_b128 v[116:119], v67 offset:96
	ds_read_b128 v[120:123], v67 offset:112
	ds_read_b128 v[70:73], v67 offset:8544
	ds_read_b128 v[74:77], v67 offset:8560
	s_waitcnt lgkmcnt(4)
	v_fmac_f32_e32 v66, v100, v156
	v_fmac_f32_e32 v68, v108, v157
	v_fmac_f32_e32 v66, v101, v158
	v_fmac_f32_e32 v68, v109, v159
	v_fmac_f32_e32 v66, v102, v160
	v_fmac_f32_e32 v68, v110, v161
	v_fmac_f32_e32 v66, v103, v162
	v_fmac_f32_e32 v68, v111, v163
	v_fmac_f32_e32 v66, v104, v164
	v_fmac_f32_e32 v68, v112, v165
	v_fmac_f32_e32 v66, v105, v166
	v_fmac_f32_e32 v68, v113, v167
	v_fmac_f32_e32 v66, v106, v168
	v_fmac_f32_e32 v68, v114, v169
	v_fmac_f32_e32 v66, v107, v170
	v_fmac_f32_e32 v68, v115, v171
	ds_read_b128 v[100:103], v67 offset:128
	ds_read_b128 v[104:107], v67 offset:144
	ds_read_b128 v[108:111], v67 offset:8576
	ds_read_b128 v[112:115], v67 offset:8592
	s_waitcnt lgkmcnt(4)
	v_fmac_f32_e32 v66, v116, v172
	v_fmac_f32_e32 v68, v70, v81
	v_fmac_f32_e32 v66, v117, v174
	v_fmac_f32_e32 v68, v71, v175
	v_fmac_f32_e32 v66, v118, v176
	v_fmac_f32_e32 v68, v72, v177
	v_fmac_f32_e32 v66, v119, v178
	v_fmac_f32_e32 v68, v73, v179
	v_fmac_f32_e32 v66, v120, v180
	v_fmac_f32_e32 v68, v74, v181
	v_fmac_f32_e32 v66, v121, v182
	v_fmac_f32_e32 v68, v75, v183
	v_fmac_f32_e32 v66, v122, v184
	v_fmac_f32_e32 v68, v76, v185
	v_fmac_f32_e32 v66, v123, v186
	v_fmac_f32_e32 v68, v77, v187
	ds_read_b128 v[116:119], v67 offset:160
	ds_read_b128 v[120:123], v67 offset:176
	ds_read_b128 v[70:73], v67 offset:8608
	ds_read_b128 v[74:77], v67 offset:8624
	s_waitcnt lgkmcnt(4)
	v_fmac_f32_e32 v66, v100, v188
	v_fmac_f32_e32 v68, v108, v189
	v_fmac_f32_e32 v66, v101, v190
	v_fmac_f32_e32 v68, v109, v191
	v_fmac_f32_e32 v66, v102, v192
	v_fmac_f32_e32 v68, v110, v193
	v_fmac_f32_e32 v66, v103, v194
	v_fmac_f32_e32 v68, v111, v195
	v_fmac_f32_e32 v66, v104, v196
	v_fmac_f32_e32 v68, v112, v197
	v_fmac_f32_e32 v66, v105, v198
	v_fmac_f32_e32 v68, v113, v199
	v_fmac_f32_e32 v66, v106, v200
	v_fmac_f32_e32 v68, v114, v201
	v_fmac_f32_e32 v66, v107, v202
	v_fmac_f32_e32 v68, v115, v203
	ds_read_b128 v[100:103], v67 offset:192
	ds_read_b128 v[104:107], v67 offset:208
	ds_read_b128 v[108:111], v67 offset:8640
	ds_read_b128 v[112:115], v67 offset:8656
	s_waitcnt lgkmcnt(4)
	v_fmac_f32_e32 v66, v116, v204
	v_fmac_f32_e32 v68, v70, v205
	v_fmac_f32_e32 v66, v117, v206
	v_fmac_f32_e32 v68, v71, v207
	v_fmac_f32_e32 v66, v118, v208
	v_fmac_f32_e32 v68, v72, v209
	v_fmac_f32_e32 v66, v119, v210
	v_fmac_f32_e32 v68, v73, v211
	v_fmac_f32_e32 v66, v120, v212
	v_fmac_f32_e32 v68, v74, v213
	v_fmac_f32_e32 v66, v121, v214
	v_fmac_f32_e32 v68, v75, v215
	v_fmac_f32_e32 v66, v122, v216
	v_fmac_f32_e32 v68, v76, v217
	v_fmac_f32_e32 v66, v123, v218
	v_fmac_f32_e32 v68, v77, v219
	ds_read_b128 v[116:119], v67 offset:224
	ds_read_b128 v[120:123], v67 offset:240
	ds_read_b128 v[70:73], v67 offset:8672
	ds_read_b128 v[74:77], v67 offset:8688
	s_waitcnt lgkmcnt(4)
	v_fmac_f32_e32 v66, v100, v220
	v_fmac_f32_e32 v68, v108, v221
	v_fmac_f32_e32 v66, v101, v222
	v_fmac_f32_e32 v68, v109, v223
	v_fmac_f32_e32 v66, v102, v224
	v_fmac_f32_e32 v68, v110, v225
	v_fmac_f32_e32 v66, v103, v226
	v_fmac_f32_e32 v68, v111, v227
	v_fmac_f32_e32 v66, v104, v228
	v_fmac_f32_e32 v68, v112, v229
	v_fmac_f32_e32 v66, v105, v230
	v_fmac_f32_e32 v68, v113, v231
	v_fmac_f32_e32 v66, v106, v232
	v_fmac_f32_e32 v68, v114, v233
	v_fmac_f32_e32 v66, v107, v234
	v_fmac_f32_e32 v68, v115, v235
	s_waitcnt lgkmcnt(0)
	v_fmac_f32_e32 v66, v116, v236
	v_fmac_f32_e32 v68, v70, v237
	v_fmac_f32_e32 v66, v117, v238
	v_fmac_f32_e32 v68, v71, v239
	v_fmac_f32_e32 v66, v118, v240
	v_fmac_f32_e32 v68, v72, v241
	v_fmac_f32_e32 v66, v119, v242
	v_fmac_f32_e32 v68, v73, v243
	v_fmac_f32_e32 v66, v120, v244
	v_fmac_f32_e32 v68, v74, v245
	v_fmac_f32_e32 v66, v121, v246
	v_fmac_f32_e32 v68, v75, v247
	v_fmac_f32_e32 v66, v122, v248
	v_fmac_f32_e32 v68, v76, v249
	v_fmac_f32_e32 v66, v123, v250
	v_fmac_f32_e32 v68, v77, v251
	v_sub_f32_e32 v66, v66, v68
	v_cmp_gt_u32_e32 vcc, s33, v64
	s_and_b64 s[48:49], s[8:9], vcc
	s_and_saveexec_b64 s[14:15], s[48:49]
	s_cbranch_execz .LBB0_32
	v_lshrrev_b32_e32 v67, 4, v64
	v_or_b32_e32 v68, s46, v67
	v_readlane_b32 s68, v252, 28
	v_ashrrev_i32_e32 v69, 31, v68
	v_readlane_b32 s70, v252, 30
	v_readlane_b32 s71, v252, 31
	v_readlane_b32 s69, v252, 29
	v_readlane_b32 s72, v252, 32
	v_lshl_add_u64 v[68:69], v[68:69], 2, s[70:71]
	global_load_dword v67, v[68:69], off
	v_readlane_b32 s73, v252, 33
	v_readlane_b32 s74, v252, 34
	v_readlane_b32 s75, v252, 35
	v_readlane_b32 s76, v252, 36
	v_readlane_b32 s77, v252, 37
	v_readlane_b32 s78, v252, 38
	v_readlane_b32 s79, v252, 39
	v_readlane_b32 s80, v252, 40
	v_readlane_b32 s81, v252, 41
	v_readlane_b32 s82, v252, 42
	v_readlane_b32 s83, v252, 43
	s_waitcnt vmcnt(0)
	v_add_f32_e32 v66, v66, v67
	s_branch .LBB0_32
